# FFN-up tile epilogue: second row block's norm partials and the eight conv weights are loaded together with the first row block's partials (two exposed global-load latencies per tile removed)
# baseline (speedup 1.0000x reference)
.LBB0_679:
	s_waitcnt lgkmcnt(1)
	v_mfma_f32_32x32x16_bf16 v[50:65], v[102:105], v[106:109], v[50:65]
	s_waitcnt vmcnt(4)
	ds_write_b128 v140, v[66:69] offset:36864
	s_waitcnt vmcnt(3)
	ds_write_b128 v140, v[74:77] offset:55296
	v_mfma_f32_32x32x16_bf16 v[34:49], v[94:97], v[106:109], v[34:49]
	ds_write_b128 v142, v[70:73] offset:36864
	s_waitcnt vmcnt(2)
	ds_write_b128 v142, v[82:85] offset:55296
	s_waitcnt lgkmcnt(4)
	v_mfma_f32_32x32x16_bf16 v[18:33], v[102:105], v[98:101], v[18:33]
	ds_write_b128 v144, v[78:81] offset:36864
	s_waitcnt vmcnt(1)
	ds_write_b128 v144, v[86:89] offset:55296
	v_mfma_f32_32x32x16_bf16 v[2:17], v[94:97], v[98:101], v[2:17]
	ds_write_b128 v146, v[90:93] offset:36864
	s_waitcnt vmcnt(0)
	ds_write_b128 v146, v[110:113] offset:55296
	ds_read_b128 v[66:69], v151 offset:23072
	ds_read_b128 v[70:73], v152 offset:4640
	s_waitcnt lgkmcnt(0)
	v_mfma_f32_32x32x16_bf16 v[2:17], v[66:69], v[70:73], v[2:17]
	ds_read_b128 v[74:77], v151 offset:18464
	ds_read_b128 v[78:81], v151 offset:18496
	s_waitcnt lgkmcnt(1)
	v_mfma_f32_32x32x16_bf16 v[18:33], v[74:77], v[70:73], v[18:33]
	ds_read_b128 v[70:73], v152 offset:32
	ds_read_b128 v[82:85], v152 offset:64
	s_waitcnt lgkmcnt(1)
	v_mfma_f32_32x32x16_bf16 v[50:65], v[74:77], v[70:73], v[50:65]
	ds_read_b128 v[74:77], v151 offset:23104
	ds_read_b128 v[86:89], v152 offset:4672
	v_mfma_f32_32x32x16_bf16 v[34:49], v[66:69], v[70:73], v[34:49]
	ds_read_b128 v[66:69], v151 offset:18528
	ds_read_b128 v[70:73], v152 offset:96
	s_waitcnt lgkmcnt(4)
	v_mfma_f32_32x32x16_bf16 v[50:65], v[78:81], v[82:85], v[50:65]
	ds_read_b128 v[90:93], v151 offset:23136
	ds_read_b128 v[94:97], v152 offset:4704
	s_waitcnt lgkmcnt(0)
	s_barrier
	v_mfma_f32_32x32x16_bf16 v[34:49], v[74:77], v[82:85], v[34:49]
	ds_read_b128 v[82:85], v168 offset:55296
	ds_read_b128 v[98:101], v169 offset:36864
	v_mfma_f32_32x32x16_bf16 v[18:33], v[78:81], v[86:89], v[18:33]
	ds_read_b128 v[78:81], v168 offset:59904
	ds_read_b128 v[102:105], v169 offset:41472
	v_mfma_f32_32x32x16_bf16 v[2:17], v[74:77], v[86:89], v[2:17]
	ds_read_b128 v[74:77], v151 offset:59936
	ds_read_b128 v[86:89], v152 offset:41504
	v_mfma_f32_32x32x16_bf16 v[50:65], v[66:69], v[70:73], v[50:65]
	ds_read_b128 v[106:109], v151 offset:55328
	ds_read_b128 v[110:113], v151 offset:55360
	v_mfma_f32_32x32x16_bf16 v[34:49], v[90:93], v[70:73], v[34:49]
	ds_read_b128 v[70:73], v152 offset:36896
	ds_read_b128 v[128:131], v152 offset:36928
	v_mfma_f32_32x32x16_bf16 v[18:33], v[66:69], v[94:97], v[18:33]
	ds_read_b128 v[66:69], v151 offset:59968
	ds_read_b128 v[132:135], v152 offset:41536
	v_mfma_f32_32x32x16_bf16 v[2:17], v[90:93], v[94:97], v[2:17]
	ds_read_b128 v[90:93], v151 offset:55392
	ds_read_b128 v[94:97], v152 offset:36960
	s_waitcnt lgkmcnt(12)
	v_mfma_f32_32x32x16_bf16 v[50:65], v[82:85], v[98:101], v[50:65]
	ds_read_b128 v[172:175], v151 offset:60000
	ds_read_b128 v[176:179], v152 offset:41568
	s_waitcnt lgkmcnt(0)
	s_barrier
	s_barrier
	v_mfma_f32_32x32x16_bf16 v[34:49], v[78:81], v[98:101], v[34:49]
	v_mfma_f32_32x32x16_bf16 v[18:33], v[82:85], v[102:105], v[18:33]
	v_mfma_f32_32x32x16_bf16 v[2:17], v[78:81], v[102:105], v[2:17]
	v_mfma_f32_32x32x16_bf16 v[50:65], v[106:109], v[70:73], v[50:65]
	v_mfma_f32_32x32x16_bf16 v[34:49], v[74:77], v[70:73], v[34:49]
	v_mfma_f32_32x32x16_bf16 v[18:33], v[106:109], v[86:89], v[18:33]
	v_mfma_f32_32x32x16_bf16 v[2:17], v[74:77], v[86:89], v[2:17]
	v_mfma_f32_32x32x16_bf16 v[50:65], v[110:113], v[128:131], v[50:65]
	v_mfma_f32_32x32x16_bf16 v[34:49], v[66:69], v[128:131], v[34:49]
	v_mfma_f32_32x32x16_bf16 v[18:33], v[110:113], v[132:135], v[18:33]
	v_mfma_f32_32x32x16_bf16 v[2:17], v[66:69], v[132:135], v[2:17]
	v_add_u32_e32 v67, s50, v148
	v_cmp_gt_u32_e32 vcc, s22, v67
	v_mov_b32_e32 v66, 0
	v_mov_b32_e32 v68, 0
	v_mfma_f32_32x32x16_bf16 v[50:65], v[90:93], v[94:97], v[50:65]
	v_mfma_f32_32x32x16_bf16 v[34:49], v[172:175], v[94:97], v[34:49]
	v_mfma_f32_32x32x16_bf16 v[18:33], v[90:93], v[176:179], v[18:33]
	v_mfma_f32_32x32x16_bf16 v[2:17], v[172:175], v[176:179], v[2:17]
	v_add_u32_e32 v212, s50, v154
	v_cmp_gt_u32_e64 s[4:5], s22, v212
	v_or_b32_e32 v212, s58, v212
	v_lshlrev_b32_e32 v212, 6, v212
	v_lshl_or_b32 v213, s14, 6, v114
	v_lshlrev_b32_e32 v213, 2, v213
	s_load_dwordx4 s[8:11], s[0:1], 0xd0
	s_and_saveexec_b64 s[6:7], s[4:5]
	global_load_dwordx4 v[196:199], v212, s[44:45]
	global_load_dwordx4 v[200:203], v212, s[44:45] offset:16
	global_load_dwordx4 v[204:207], v212, s[44:45] offset:32
	global_load_dwordx4 v[208:211], v212, s[44:45] offset:48
	s_mov_b64 exec, s[6:7]
	s_waitcnt lgkmcnt(0)
	global_load_dword v188, v213, s[8:9]
	s_add_u32 s4, s8, s24
	s_addc_u32 s5, s9, 0
	global_load_dword v189, v213, s[4:5] offset:2048
	s_add_u32 s4, s8, s28
	s_addc_u32 s5, s9, 0
	global_load_dword v190, v213, s[4:5]
	global_load_dword v191, v213, s[10:11]
	s_add_u32 s4, s8, s22
	s_addc_u32 s5, s9, 0
	global_load_dword v192, v213, s[4:5] offset:3072
	s_add_u32 s4, s8, s29
	s_addc_u32 s5, s9, 0
	global_load_dword v193, v213, s[4:5] offset:1024
	s_add_u32 s4, s8, s33
	s_addc_u32 s5, s9, 0
	global_load_dword v194, v213, s[4:5] offset:3072
	s_add_u32 s4, s10, s22
	s_addc_u32 s5, s11, 0
	global_load_dword v195, v213, s[4:5] offset:3072
	s_and_saveexec_b64 s[4:5], vcc
	s_cbranch_execz .LBB0_681
	v_or_b32_e32 v67, s58, v67
	v_lshlrev_b32_e32 v67, 6, v67
	global_load_dwordx4 v[68:71], v67, s[44:45]
	global_load_dwordx4 v[72:75], v67, s[44:45] offset:16
	global_load_dwordx4 v[76:79], v67, s[44:45] offset:32
	global_load_dwordx4 v[80:83], v67, s[44:45] offset:48
	s_waitcnt vmcnt(3)
	v_mov_b32_e32 v84, v69
	v_mov_b32_e32 v85, v70
	v_mov_b32_e32 v69, v71
	s_waitcnt vmcnt(2)
	v_mov_b32_e32 v70, v73
	v_mov_b32_e32 v71, v74
	v_mov_b32_e32 v73, v75
	v_pk_add_f32 v[68:69], v[84:85], v[68:69]
	v_pk_add_f32 v[70:71], v[70:71], v[72:73]
	v_pk_add_f32 v[68:69], v[68:69], v[68:69] op_sel:[0,1] op_sel_hi:[1,0]
	v_pk_add_f32 v[70:71], v[70:71], v[70:71] op_sel:[0,1] op_sel_hi:[1,0]
	s_waitcnt vmcnt(1)
	v_add_f32_e32 v74, v76, v77
	v_add_f32_e32 v76, v78, v79
	s_waitcnt vmcnt(0)
	v_mov_b32_e32 v75, v82
	v_mov_b32_e32 v77, v83
	v_mov_b32_e32 v69, v80
	v_mov_b32_e32 v71, v81
	v_pk_add_f32 v[72:73], v[74:75], v[76:77]
	v_pk_add_f32 v[68:69], v[68:69], v[70:71]
	s_nop 0
	v_pk_add_f32 v[68:69], v[68:69], v[72:73]
	s_nop 0
	v_add_f32_e32 v67, v68, v69
	v_fmamk_f32 v67, v67, 0x3a800000, v170
	v_mul_f32_e32 v68, 0x4b800000, v67
	v_cmp_gt_f32_e32 vcc, s25, v67
	s_nop 1
	v_cndmask_b32_e32 v67, v67, v68, vcc
	v_rsq_f32_e32 v67, v67
	s_nop 0
	v_mul_f32_e32 v68, 0x45800000, v67
	v_cndmask_b32_e32 v68, v67, v68, vcc
.LBB0_681:
	s_or_b64 exec, exec, s[4:5]
	s_nop 6
	v_pk_mul_f32 v[34:35], v[34:35], v[68:69] op_sel_hi:[1,0]
	ds_write2_b32 v153, v34, v35 offset0:32 offset1:33
	v_pk_mul_f32 v[34:35], v[36:37], v[68:69] op_sel_hi:[1,0]
	v_pk_mul_f32 v[50:51], v[50:51], v[68:69] op_sel_hi:[1,0]
	ds_write2_b32 v153, v34, v35 offset0:34 offset1:35
	v_pk_mul_f32 v[34:35], v[38:39], v[68:69] op_sel_hi:[1,0]
	ds_write2_b32 v153, v50, v51 offset1:1
	v_pk_mul_f32 v[50:51], v[52:53], v[68:69] op_sel_hi:[1,0]
	ds_write2_b32 v153, v34, v35 offset0:40 offset1:41
	v_pk_mul_f32 v[34:35], v[40:41], v[68:69] op_sel_hi:[1,0]
	ds_write2_b32 v153, v50, v51 offset0:2 offset1:3
	v_pk_mul_f32 v[50:51], v[54:55], v[68:69] op_sel_hi:[1,0]
	ds_write2_b32 v153, v34, v35 offset0:42 offset1:43
	v_pk_mul_f32 v[34:35], v[42:43], v[68:69] op_sel_hi:[1,0]
	ds_write2_b32 v153, v50, v51 offset0:8 offset1:9
	v_pk_mul_f32 v[50:51], v[56:57], v[68:69] op_sel_hi:[1,0]
	ds_write2_b32 v153, v34, v35 offset0:48 offset1:49
	v_pk_mul_f32 v[34:35], v[44:45], v[68:69] op_sel_hi:[1,0]
	ds_write2_b32 v153, v50, v51 offset0:10 offset1:11
	v_pk_mul_f32 v[50:51], v[58:59], v[68:69] op_sel_hi:[1,0]
	ds_write2_b32 v153, v34, v35 offset0:50 offset1:51
	v_pk_mul_f32 v[34:35], v[46:47], v[68:69] op_sel_hi:[1,0]
	ds_write2_b32 v153, v50, v51 offset0:16 offset1:17
	v_pk_mul_f32 v[50:51], v[60:61], v[68:69] op_sel_hi:[1,0]
	ds_write2_b32 v153, v34, v35 offset0:56 offset1:57
	v_pk_mul_f32 v[34:35], v[48:49], v[68:69] op_sel_hi:[1,0]
	ds_write2_b32 v153, v50, v51 offset0:18 offset1:19
	v_pk_mul_f32 v[50:51], v[62:63], v[68:69] op_sel_hi:[1,0]
	ds_write2_b32 v153, v34, v35 offset0:58 offset1:59
	v_add_u32_e32 v34, s50, v154
	ds_write2_b32 v153, v50, v51 offset0:24 offset1:25
	v_pk_mul_f32 v[50:51], v[64:65], v[68:69] op_sel_hi:[1,0]
	v_cmp_gt_u32_e32 vcc, s22, v34
	ds_write2_b32 v153, v50, v51 offset0:26 offset1:27
	s_and_saveexec_b64 s[4:5], vcc
	s_cbranch_execz .LBB0_683
	v_or_b32_e32 v34, s58, v34
	v_lshlrev_b32_e32 v46, 6, v34
	s_waitcnt vmcnt(0)
	v_mov_b32_e32 v34, v196
	v_mov_b32_e32 v35, v197
	v_mov_b32_e32 v36, v198
	v_mov_b32_e32 v37, v199
	v_mov_b32_e32 v38, v200
	v_mov_b32_e32 v39, v201
	v_mov_b32_e32 v40, v202
	v_mov_b32_e32 v41, v203
	v_mov_b32_e32 v42, v204
	v_mov_b32_e32 v43, v205
	v_mov_b32_e32 v44, v206
	v_mov_b32_e32 v45, v207
	v_mov_b32_e32 v46, v208
	v_mov_b32_e32 v47, v209
	v_mov_b32_e32 v48, v210
	v_mov_b32_e32 v49, v211
	s_waitcnt vmcnt(3)
	v_mov_b32_e32 v50, v35
	v_mov_b32_e32 v51, v36
	v_mov_b32_e32 v35, v37
	s_waitcnt vmcnt(2)
	v_mov_b32_e32 v36, v39
	v_mov_b32_e32 v37, v40
	v_mov_b32_e32 v39, v41
	v_pk_add_f32 v[34:35], v[50:51], v[34:35]
	v_pk_add_f32 v[36:37], v[36:37], v[38:39]
	v_pk_add_f32 v[34:35], v[34:35], v[34:35] op_sel:[0,1] op_sel_hi:[1,0]
	v_pk_add_f32 v[36:37], v[36:37], v[36:37] op_sel:[0,1] op_sel_hi:[1,0]
	s_waitcnt vmcnt(1)
	v_add_f32_e32 v40, v42, v43
	v_add_f32_e32 v42, v44, v45
	s_waitcnt vmcnt(0)
	v_mov_b32_e32 v41, v48
	v_mov_b32_e32 v43, v49
	v_mov_b32_e32 v35, v46
	v_mov_b32_e32 v37, v47
	v_pk_add_f32 v[38:39], v[40:41], v[42:43]
	v_pk_add_f32 v[34:35], v[34:35], v[36:37]
	s_nop 0
	v_pk_add_f32 v[34:35], v[34:35], v[38:39]
	s_nop 0
	v_add_f32_e32 v34, v34, v35
	v_fmamk_f32 v34, v34, 0x3a800000, v170
	v_mul_f32_e32 v35, 0x4b800000, v34
	v_cmp_gt_f32_e32 vcc, s25, v34
	s_nop 1
	v_cndmask_b32_e32 v34, v34, v35, vcc
	v_rsq_f32_e32 v34, v34
	s_nop 0
	v_mul_f32_e32 v35, 0x45800000, v34
	v_cndmask_b32_e32 v66, v34, v35, vcc
.LBB0_683:
	s_or_b64 exec, exec, s[4:5]
	v_pk_mul_f32 v[2:3], v[2:3], v[66:67] op_sel_hi:[1,0]
	ds_write2_b32 v155, v2, v3 offset0:32 offset1:33
	v_pk_mul_f32 v[2:3], v[4:5], v[66:67] op_sel_hi:[1,0]
	ds_write2_b32 v155, v2, v3 offset0:34 offset1:35
	v_pk_mul_f32 v[2:3], v[6:7], v[66:67] op_sel_hi:[1,0]
	ds_write2_b32 v155, v2, v3 offset0:40 offset1:41
	v_pk_mul_f32 v[2:3], v[8:9], v[66:67] op_sel_hi:[1,0]
	ds_write2_b32 v155, v2, v3 offset0:42 offset1:43
	v_pk_mul_f32 v[2:3], v[10:11], v[66:67] op_sel_hi:[1,0]
	ds_write2_b32 v155, v2, v3 offset0:48 offset1:49
	v_pk_mul_f32 v[2:3], v[12:13], v[66:67] op_sel_hi:[1,0]
	s_load_dwordx8 s[4:11], s[0:1], 0xc0
	ds_write2_b32 v155, v2, v3 offset0:50 offset1:51
	v_pk_mul_f32 v[2:3], v[14:15], v[66:67] op_sel_hi:[1,0]
	ds_write2_b32 v155, v2, v3 offset0:56 offset1:57
	v_pk_mul_f32 v[2:3], v[16:17], v[66:67] op_sel_hi:[1,0]
	ds_write2_b32 v155, v2, v3 offset0:58 offset1:59
	v_lshl_or_b32 v2, s14, 6, v114
	v_ashrrev_i32_e32 v3, 31, v2
	v_lshlrev_b64 v[8:9], 2, v[2:3]
	s_waitcnt lgkmcnt(0)
	s_mov_b64 s[4:5], s[8:9]
	v_lshl_add_u64 v[10:11], s[4:5], 0, v[8:9]
	v_pk_mul_f32 v[18:19], v[18:19], v[66:67] op_sel_hi:[1,0]
	v_add_co_u32_e32 v4, vcc, s24, v10
	ds_write2_b32 v155, v18, v19 offset1:1
	v_pk_mul_f32 v[18:19], v[20:21], v[66:67] op_sel_hi:[1,0]
	v_addc_co_u32_e32 v5, vcc, 0, v11, vcc
	ds_write2_b32 v155, v18, v19 offset0:2 offset1:3
	v_pk_mul_f32 v[18:19], v[22:23], v[66:67] op_sel_hi:[1,0]
	v_add_co_u32_e32 v6, vcc, s28, v10
	ds_write2_b32 v155, v18, v19 offset0:8 offset1:9
	v_pk_mul_f32 v[18:19], v[24:25], v[66:67] op_sel_hi:[1,0]
	v_addc_co_u32_e32 v7, vcc, 0, v11, vcc
	ds_write2_b32 v155, v18, v19 offset0:10 offset1:11
	v_pk_mul_f32 v[18:19], v[26:27], v[66:67] op_sel_hi:[1,0]
	v_add_co_u32_e32 v14, vcc, s22, v10
	ds_write2_b32 v155, v18, v19 offset0:16 offset1:17
	v_pk_mul_f32 v[18:19], v[28:29], v[66:67] op_sel_hi:[1,0]
	v_addc_co_u32_e32 v15, vcc, 0, v11, vcc
	ds_write2_b32 v155, v18, v19 offset0:18 offset1:19
	v_pk_mul_f32 v[18:19], v[30:31], v[66:67] op_sel_hi:[1,0]
	v_add_co_u32_e32 v16, vcc, s29, v10
	ds_write2_b32 v155, v18, v19 offset0:24 offset1:25
	v_pk_mul_f32 v[18:19], v[32:33], v[66:67] op_sel_hi:[1,0]
	v_addc_co_u32_e32 v17, vcc, 0, v11, vcc
	ds_write2_b32 v155, v18, v19 offset0:26 offset1:27
	s_waitcnt lgkmcnt(0)
	s_barrier
	s_mov_b64 s[6:7], s[10:11]
	s_waitcnt vmcnt(0)
	v_mov_b32_e32 v3, v188
	s_nop 0
	v_mov_b32_e32 v5, v189
	s_nop 0
	v_mov_b32_e32 v7, v190
	v_add_co_u32_e32 v10, vcc, s33, v10
	v_lshl_add_u64 v[12:13], s[6:7], 0, v[8:9]
	s_nop 0
	v_addc_co_u32_e32 v11, vcc, 0, v11, vcc
	v_mov_b32_e32 v9, v191
	v_mov_b32_e32 v2, v192
	v_mov_b32_e32 v4, v193
	v_mov_b32_e32 v6, v194
	v_add_co_u32_e32 v10, vcc, s22, v12
	s_mul_i32 s4, s51, 0x7e
	s_nop 0
	v_addc_co_u32_e32 v11, vcc, 0, v13, vcc
	v_mov_b32_e32 v8, v195
	ds_read_b32 v15, v159
	ds_read_b32 v10, v160
	ds_read_b32 v14, v161
	ds_read_b32 v11, v162
	s_add_i32 s4, s21, s4
	s_mulk_i32 s52, 0x7c
	s_sub_i32 s10, s4, s52
	v_add_lshl_u32 v16, v167, s53, 6
	s_mov_b64 s[4:5], 0
	v_mov_b32_e32 v17, v158
	v_mov_b32_e32 v18, v156
	s_waitcnt vmcnt(0)
	s_add_i32 s63, s10, -2
	s_sub_i32 s64, s22, s50
	v_min_i32_e32 v40, s64, v157
	v_add_u32_e32 v40, s63, v40
	v_lshlrev_b32_e32 v41, 1, v114
	s_mov_b32 s62, 4

.LBB0_2396:
	s_waitcnt lgkmcnt(1)
	v_mfma_f32_32x32x16_bf16 v[50:65], v[102:105], v[106:109], v[50:65]
	s_waitcnt vmcnt(4)
	ds_write_b128 v140, v[66:69] offset:36864
	s_waitcnt vmcnt(3)
	ds_write_b128 v140, v[74:77] offset:55296
	v_mfma_f32_32x32x16_bf16 v[34:49], v[94:97], v[106:109], v[34:49]
	ds_write_b128 v142, v[70:73] offset:36864
	s_waitcnt vmcnt(2)
	ds_write_b128 v142, v[82:85] offset:55296
	s_waitcnt lgkmcnt(4)
	v_mfma_f32_32x32x16_bf16 v[18:33], v[102:105], v[98:101], v[18:33]
	ds_write_b128 v144, v[78:81] offset:36864
	s_waitcnt vmcnt(1)
	ds_write_b128 v144, v[86:89] offset:55296
	v_mfma_f32_32x32x16_bf16 v[2:17], v[94:97], v[98:101], v[2:17]
	ds_write_b128 v146, v[90:93] offset:36864
	s_waitcnt vmcnt(0)
	ds_write_b128 v146, v[110:113] offset:55296
	ds_read_b128 v[66:69], v151 offset:23072
	ds_read_b128 v[70:73], v152 offset:4640
	s_waitcnt lgkmcnt(0)
	v_mfma_f32_32x32x16_bf16 v[2:17], v[66:69], v[70:73], v[2:17]
	ds_read_b128 v[74:77], v151 offset:18464
	ds_read_b128 v[78:81], v151 offset:18496
	s_waitcnt lgkmcnt(1)
	v_mfma_f32_32x32x16_bf16 v[18:33], v[74:77], v[70:73], v[18:33]
	ds_read_b128 v[70:73], v152 offset:32
	ds_read_b128 v[82:85], v152 offset:64
	s_waitcnt lgkmcnt(1)
	v_mfma_f32_32x32x16_bf16 v[50:65], v[74:77], v[70:73], v[50:65]
	ds_read_b128 v[74:77], v151 offset:23104
	ds_read_b128 v[86:89], v152 offset:4672
	v_mfma_f32_32x32x16_bf16 v[34:49], v[66:69], v[70:73], v[34:49]
	ds_read_b128 v[66:69], v151 offset:18528
	ds_read_b128 v[70:73], v152 offset:96
	s_waitcnt lgkmcnt(4)
	v_mfma_f32_32x32x16_bf16 v[50:65], v[78:81], v[82:85], v[50:65]
	ds_read_b128 v[90:93], v151 offset:23136
	ds_read_b128 v[94:97], v152 offset:4704
	s_waitcnt lgkmcnt(0)
	s_barrier
	v_mfma_f32_32x32x16_bf16 v[34:49], v[74:77], v[82:85], v[34:49]
	ds_read_b128 v[82:85], v168 offset:55296
	ds_read_b128 v[98:101], v169 offset:36864
	v_mfma_f32_32x32x16_bf16 v[18:33], v[78:81], v[86:89], v[18:33]
	ds_read_b128 v[78:81], v168 offset:59904
	ds_read_b128 v[102:105], v169 offset:41472
	v_mfma_f32_32x32x16_bf16 v[2:17], v[74:77], v[86:89], v[2:17]
	ds_read_b128 v[74:77], v151 offset:59936
	ds_read_b128 v[86:89], v152 offset:41504
	v_mfma_f32_32x32x16_bf16 v[50:65], v[66:69], v[70:73], v[50:65]
	ds_read_b128 v[106:109], v151 offset:55328
	ds_read_b128 v[110:113], v151 offset:55360
	v_mfma_f32_32x32x16_bf16 v[34:49], v[90:93], v[70:73], v[34:49]
	ds_read_b128 v[70:73], v152 offset:36896
	ds_read_b128 v[128:131], v152 offset:36928
	v_mfma_f32_32x32x16_bf16 v[18:33], v[66:69], v[94:97], v[18:33]
	ds_read_b128 v[66:69], v151 offset:59968
	ds_read_b128 v[132:135], v152 offset:41536
	v_mfma_f32_32x32x16_bf16 v[2:17], v[90:93], v[94:97], v[2:17]
	ds_read_b128 v[90:93], v151 offset:55392
	ds_read_b128 v[94:97], v152 offset:36960
	s_waitcnt lgkmcnt(12)
	v_mfma_f32_32x32x16_bf16 v[50:65], v[82:85], v[98:101], v[50:65]
	ds_read_b128 v[172:175], v151 offset:60000
	ds_read_b128 v[176:179], v152 offset:41568
	s_waitcnt lgkmcnt(0)
	s_barrier
	s_barrier
	v_mfma_f32_32x32x16_bf16 v[34:49], v[78:81], v[98:101], v[34:49]
	v_mfma_f32_32x32x16_bf16 v[18:33], v[82:85], v[102:105], v[18:33]
	v_mfma_f32_32x32x16_bf16 v[2:17], v[78:81], v[102:105], v[2:17]
	v_mfma_f32_32x32x16_bf16 v[50:65], v[106:109], v[70:73], v[50:65]
	v_mfma_f32_32x32x16_bf16 v[34:49], v[74:77], v[70:73], v[34:49]
	v_mfma_f32_32x32x16_bf16 v[18:33], v[106:109], v[86:89], v[18:33]
	v_mfma_f32_32x32x16_bf16 v[2:17], v[74:77], v[86:89], v[2:17]
	v_mfma_f32_32x32x16_bf16 v[50:65], v[110:113], v[128:131], v[50:65]
	v_mfma_f32_32x32x16_bf16 v[34:49], v[66:69], v[128:131], v[34:49]
	v_mfma_f32_32x32x16_bf16 v[18:33], v[110:113], v[132:135], v[18:33]
	v_mfma_f32_32x32x16_bf16 v[2:17], v[66:69], v[132:135], v[2:17]
	v_add_u32_e32 v67, s36, v148
	v_cmp_gt_u32_e32 vcc, s26, v67
	v_mov_b32_e32 v66, 0
	v_mov_b32_e32 v68, 0
	v_mfma_f32_32x32x16_bf16 v[50:65], v[90:93], v[94:97], v[50:65]
	v_mfma_f32_32x32x16_bf16 v[34:49], v[172:175], v[94:97], v[34:49]
	v_mfma_f32_32x32x16_bf16 v[18:33], v[90:93], v[176:179], v[18:33]
	v_mfma_f32_32x32x16_bf16 v[2:17], v[172:175], v[176:179], v[2:17]
	v_add_u32_e32 v212, s36, v154
	v_cmp_gt_u32_e64 s[4:5], s26, v212
	v_or_b32_e32 v212, s40, v212
	v_lshlrev_b32_e32 v212, 6, v212
	v_lshl_or_b32 v213, s18, 6, v114
	v_lshlrev_b32_e32 v213, 2, v213
	s_and_saveexec_b64 s[6:7], s[4:5]
	global_load_dwordx4 v[196:199], v212, s[44:45]
	global_load_dwordx4 v[200:203], v212, s[44:45] offset:16
	global_load_dwordx4 v[204:207], v212, s[44:45] offset:32
	global_load_dwordx4 v[208:211], v212, s[44:45] offset:48
	s_mov_b64 exec, s[6:7]
	global_load_dword v188, v213, s[14:15]
	s_add_u32 s4, s14, s28
	s_addc_u32 s5, s15, 0
	global_load_dword v189, v213, s[4:5] offset:2048
	s_add_u32 s4, s14, s30
	s_addc_u32 s5, s15, 0
	global_load_dword v190, v213, s[4:5]
	global_load_dword v191, v213, s[16:17]
	s_add_u32 s4, s14, s26
	s_addc_u32 s5, s15, 0
	global_load_dword v192, v213, s[4:5] offset:3072
	s_add_u32 s4, s14, s31
	s_addc_u32 s5, s15, 0
	global_load_dword v193, v213, s[4:5] offset:1024
	s_add_u32 s4, s14, s33
	s_addc_u32 s5, s15, 0
	global_load_dword v194, v213, s[4:5] offset:3072
	s_add_u32 s4, s16, s26
	s_addc_u32 s5, s17, 0
	global_load_dword v195, v213, s[4:5] offset:3072
	s_and_saveexec_b64 s[4:5], vcc
	s_cbranch_execz .LBB0_2398
	v_or_b32_e32 v67, s40, v67
	v_lshlrev_b32_e32 v67, 6, v67
	global_load_dwordx4 v[68:71], v67, s[44:45]
	global_load_dwordx4 v[72:75], v67, s[44:45] offset:16
	global_load_dwordx4 v[76:79], v67, s[44:45] offset:32
	global_load_dwordx4 v[80:83], v67, s[44:45] offset:48
	s_waitcnt vmcnt(3)
	v_mov_b32_e32 v84, v69
	v_mov_b32_e32 v85, v70
	v_mov_b32_e32 v69, v71
	s_waitcnt vmcnt(2)
	v_mov_b32_e32 v70, v73
	v_mov_b32_e32 v71, v74
	v_mov_b32_e32 v73, v75
	v_pk_add_f32 v[68:69], v[84:85], v[68:69]
	v_pk_add_f32 v[70:71], v[70:71], v[72:73]
	v_pk_add_f32 v[68:69], v[68:69], v[68:69] op_sel:[0,1] op_sel_hi:[1,0]
	v_pk_add_f32 v[70:71], v[70:71], v[70:71] op_sel:[0,1] op_sel_hi:[1,0]
	s_waitcnt vmcnt(1)
	v_add_f32_e32 v74, v76, v77
	v_add_f32_e32 v76, v78, v79
	s_waitcnt vmcnt(0)
	v_mov_b32_e32 v75, v82
	v_mov_b32_e32 v77, v83
	v_mov_b32_e32 v69, v80
	v_mov_b32_e32 v71, v81
	v_pk_add_f32 v[72:73], v[74:75], v[76:77]
	v_pk_add_f32 v[68:69], v[68:69], v[70:71]
	s_nop 0
	v_pk_add_f32 v[68:69], v[68:69], v[72:73]
	s_nop 0
	v_add_f32_e32 v67, v68, v69
	v_fmamk_f32 v67, v67, 0x3a800000, v170
	v_mul_f32_e32 v68, 0x4b800000, v67
	v_cmp_gt_f32_e32 vcc, s29, v67
	s_nop 1
	v_cndmask_b32_e32 v67, v67, v68, vcc
	v_rsq_f32_e32 v67, v67
	s_nop 0
	v_mul_f32_e32 v68, 0x45800000, v67
	v_cndmask_b32_e32 v68, v67, v68, vcc
.LBB0_2398:
	s_or_b64 exec, exec, s[4:5]
	s_nop 6
	v_pk_mul_f32 v[34:35], v[34:35], v[68:69] op_sel_hi:[1,0]
	ds_write2_b32 v153, v34, v35 offset0:32 offset1:33
	v_pk_mul_f32 v[34:35], v[36:37], v[68:69] op_sel_hi:[1,0]
	v_pk_mul_f32 v[50:51], v[50:51], v[68:69] op_sel_hi:[1,0]
	ds_write2_b32 v153, v34, v35 offset0:34 offset1:35
	v_pk_mul_f32 v[34:35], v[38:39], v[68:69] op_sel_hi:[1,0]
	ds_write2_b32 v153, v50, v51 offset1:1
	v_pk_mul_f32 v[50:51], v[52:53], v[68:69] op_sel_hi:[1,0]
	ds_write2_b32 v153, v34, v35 offset0:40 offset1:41
	v_pk_mul_f32 v[34:35], v[40:41], v[68:69] op_sel_hi:[1,0]
	ds_write2_b32 v153, v50, v51 offset0:2 offset1:3
	v_pk_mul_f32 v[50:51], v[54:55], v[68:69] op_sel_hi:[1,0]
	ds_write2_b32 v153, v34, v35 offset0:42 offset1:43
	v_pk_mul_f32 v[34:35], v[42:43], v[68:69] op_sel_hi:[1,0]
	ds_write2_b32 v153, v50, v51 offset0:8 offset1:9
	v_pk_mul_f32 v[50:51], v[56:57], v[68:69] op_sel_hi:[1,0]
	ds_write2_b32 v153, v34, v35 offset0:48 offset1:49
	v_pk_mul_f32 v[34:35], v[44:45], v[68:69] op_sel_hi:[1,0]
	ds_write2_b32 v153, v50, v51 offset0:10 offset1:11
	v_pk_mul_f32 v[50:51], v[58:59], v[68:69] op_sel_hi:[1,0]
	ds_write2_b32 v153, v34, v35 offset0:50 offset1:51
	v_pk_mul_f32 v[34:35], v[46:47], v[68:69] op_sel_hi:[1,0]
	ds_write2_b32 v153, v50, v51 offset0:16 offset1:17
	v_pk_mul_f32 v[50:51], v[60:61], v[68:69] op_sel_hi:[1,0]
	ds_write2_b32 v153, v34, v35 offset0:56 offset1:57
	v_pk_mul_f32 v[34:35], v[48:49], v[68:69] op_sel_hi:[1,0]
	ds_write2_b32 v153, v50, v51 offset0:18 offset1:19
	v_pk_mul_f32 v[50:51], v[62:63], v[68:69] op_sel_hi:[1,0]
	ds_write2_b32 v153, v34, v35 offset0:58 offset1:59
	v_add_u32_e32 v34, s36, v154
	ds_write2_b32 v153, v50, v51 offset0:24 offset1:25
	v_pk_mul_f32 v[50:51], v[64:65], v[68:69] op_sel_hi:[1,0]
	v_cmp_gt_u32_e32 vcc, s26, v34
	ds_write2_b32 v153, v50, v51 offset0:26 offset1:27
	s_and_saveexec_b64 s[4:5], vcc
	s_cbranch_execz .LBB0_2400
	v_or_b32_e32 v34, s40, v34
	v_lshlrev_b32_e32 v50, 6, v34
	s_waitcnt vmcnt(0)
	v_mov_b32_e32 v34, v196
	v_mov_b32_e32 v35, v197
	v_mov_b32_e32 v36, v198
	v_mov_b32_e32 v37, v199
	v_mov_b32_e32 v38, v200
	v_mov_b32_e32 v39, v201
	v_mov_b32_e32 v40, v202
	v_mov_b32_e32 v41, v203
	v_mov_b32_e32 v42, v204
	v_mov_b32_e32 v43, v205
	v_mov_b32_e32 v44, v206
	v_mov_b32_e32 v45, v207
	v_mov_b32_e32 v46, v208
	v_mov_b32_e32 v47, v209
	v_mov_b32_e32 v48, v210
	v_mov_b32_e32 v49, v211
	s_waitcnt vmcnt(3)
	v_mov_b32_e32 v50, v35
	v_mov_b32_e32 v51, v36
	v_mov_b32_e32 v35, v37
	s_waitcnt vmcnt(2)
	v_mov_b32_e32 v36, v39
	v_mov_b32_e32 v37, v40
	v_mov_b32_e32 v39, v41
	v_pk_add_f32 v[34:35], v[50:51], v[34:35]
	v_pk_add_f32 v[36:37], v[36:37], v[38:39]
	v_pk_add_f32 v[34:35], v[34:35], v[34:35] op_sel:[0,1] op_sel_hi:[1,0]
	v_pk_add_f32 v[36:37], v[36:37], v[36:37] op_sel:[0,1] op_sel_hi:[1,0]
	s_waitcnt vmcnt(1)
	v_add_f32_e32 v40, v42, v43
	v_add_f32_e32 v42, v44, v45
	s_waitcnt vmcnt(0)
	v_mov_b32_e32 v41, v48
	v_mov_b32_e32 v43, v49
	v_mov_b32_e32 v35, v46
	v_mov_b32_e32 v37, v47
	v_pk_add_f32 v[38:39], v[40:41], v[42:43]
	v_pk_add_f32 v[34:35], v[34:35], v[36:37]
	s_nop 0
	v_pk_add_f32 v[34:35], v[34:35], v[38:39]
	s_nop 0
	v_add_f32_e32 v34, v34, v35
	v_fmamk_f32 v34, v34, 0x3a800000, v170
	v_mul_f32_e32 v35, 0x4b800000, v34
	v_cmp_gt_f32_e32 vcc, s29, v34
	s_nop 1
	v_cndmask_b32_e32 v34, v34, v35, vcc
	v_rsq_f32_e32 v34, v34
	s_nop 0
	v_mul_f32_e32 v35, 0x45800000, v34
	v_cndmask_b32_e32 v66, v34, v35, vcc
.LBB0_2400:
	s_or_b64 exec, exec, s[4:5]
	v_pk_mul_f32 v[2:3], v[2:3], v[66:67] op_sel_hi:[1,0]
	ds_write2_b32 v155, v2, v3 offset0:32 offset1:33
	v_pk_mul_f32 v[2:3], v[4:5], v[66:67] op_sel_hi:[1,0]
	ds_write2_b32 v155, v2, v3 offset0:34 offset1:35
	v_pk_mul_f32 v[2:3], v[6:7], v[66:67] op_sel_hi:[1,0]
	ds_write2_b32 v155, v2, v3 offset0:40 offset1:41
	v_pk_mul_f32 v[2:3], v[8:9], v[66:67] op_sel_hi:[1,0]
	ds_write2_b32 v155, v2, v3 offset0:42 offset1:43
	v_pk_mul_f32 v[2:3], v[10:11], v[66:67] op_sel_hi:[1,0]
	ds_write2_b32 v155, v2, v3 offset0:48 offset1:49
	v_pk_mul_f32 v[2:3], v[12:13], v[66:67] op_sel_hi:[1,0]
	ds_write2_b32 v155, v2, v3 offset0:50 offset1:51
	v_pk_mul_f32 v[2:3], v[14:15], v[66:67] op_sel_hi:[1,0]
	ds_write2_b32 v155, v2, v3 offset0:56 offset1:57
	v_pk_mul_f32 v[2:3], v[16:17], v[66:67] op_sel_hi:[1,0]
	v_pk_mul_f32 v[18:19], v[18:19], v[66:67] op_sel_hi:[1,0]
	ds_write2_b32 v155, v2, v3 offset0:58 offset1:59
	v_lshl_or_b32 v2, s18, 6, v114
	ds_write2_b32 v155, v18, v19 offset1:1
	v_pk_mul_f32 v[18:19], v[20:21], v[66:67] op_sel_hi:[1,0]
	v_ashrrev_i32_e32 v3, 31, v2
	ds_write2_b32 v155, v18, v19 offset0:2 offset1:3
	v_pk_mul_f32 v[18:19], v[22:23], v[66:67] op_sel_hi:[1,0]
	v_lshlrev_b64 v[8:9], 2, v[2:3]
	ds_write2_b32 v155, v18, v19 offset0:8 offset1:9
	v_pk_mul_f32 v[18:19], v[24:25], v[66:67] op_sel_hi:[1,0]
	v_lshl_add_u64 v[10:11], s[14:15], 0, v[8:9]
	ds_write2_b32 v155, v18, v19 offset0:10 offset1:11
	v_pk_mul_f32 v[18:19], v[26:27], v[66:67] op_sel_hi:[1,0]
	v_add_co_u32_e32 v12, vcc, s28, v10
	ds_write2_b32 v155, v18, v19 offset0:16 offset1:17
	v_pk_mul_f32 v[18:19], v[28:29], v[66:67] op_sel_hi:[1,0]
	v_addc_co_u32_e32 v13, vcc, 0, v11, vcc
	ds_write2_b32 v155, v18, v19 offset0:18 offset1:19
	v_pk_mul_f32 v[18:19], v[30:31], v[66:67] op_sel_hi:[1,0]
	v_add_co_u32_e32 v14, vcc, s30, v10
	ds_write2_b32 v155, v18, v19 offset0:24 offset1:25
	v_pk_mul_f32 v[18:19], v[32:33], v[66:67] op_sel_hi:[1,0]
	v_addc_co_u32_e32 v15, vcc, 0, v11, vcc
	ds_write2_b32 v155, v18, v19 offset0:26 offset1:27
	s_waitcnt lgkmcnt(0)
	s_barrier
	s_waitcnt vmcnt(0)
	v_mov_b32_e32 v3, v188
	v_mov_b32_e32 v5, v189
	v_mov_b32_e32 v7, v190
	v_add_co_u32_e32 v14, vcc, s26, v10
	v_lshl_add_u64 v[12:13], s[16:17], 0, v[8:9]
	s_nop 0
	v_addc_co_u32_e32 v15, vcc, 0, v11, vcc
	v_add_co_u32_e32 v16, vcc, s31, v10
	v_mov_b32_e32 v9, v191
	s_nop 0
	v_addc_co_u32_e32 v17, vcc, 0, v11, vcc
	v_add_co_u32_e32 v10, vcc, s33, v10
	s_mul_i32 s4, s37, 0x7e
	s_nop 0
	v_addc_co_u32_e32 v11, vcc, 0, v11, vcc
	v_mov_b32_e32 v2, v192
	v_mov_b32_e32 v4, v193
	v_mov_b32_e32 v6, v194
	v_add_co_u32_e32 v10, vcc, s26, v12
	s_add_i32 s4, s25, s4
	s_nop 0
	v_addc_co_u32_e32 v11, vcc, 0, v13, vcc
	v_mov_b32_e32 v8, v195
	ds_read_b32 v15, v159
	ds_read_b32 v10, v160
	ds_read_b32 v14, v161
	ds_read_b32 v11, v162
	s_mulk_i32 s38, 0x7c
	s_sub_i32 s10, s4, s38
	v_add_lshl_u32 v16, v167, s39, 6
	s_mov_b64 s[4:5], 0
	v_mov_b32_e32 v17, v158
	v_mov_b32_e32 v18, v156
	s_waitcnt vmcnt(0)
	s_add_i32 s63, s10, -2
	s_sub_i32 s64, s26, s36
	v_min_i32_e32 v40, s64, v157
	v_add_u32_e32 v40, s63, v40
	v_lshlrev_b32_e32 v41, 1, v114
	s_mov_b32 s62, 4
